# W1 compress GEMMs for k and v run concurrently on different workgroups (blocks 0-15 and 128-143)
# speedup vs baseline: 1.0281x; 1.0281x over previous
; #define LDSP(T, p) ((__attribute__((address_space(3))) T*)(p))
; DI int tidx() { int t = threadIdx.x; asm volatile("" : "+v"(t)); return t; }
; DI void gemm_issue_first(const bf16_t* __restrict__ A, int lda, const bf16_t* __restrict__ Bt, int ldb, int m0, int n0, char* smem) {
;   const int tid = tidx(), wave = tid >> 6, lane = tid & 63;
; #pragma unroll
;   for (int i = 0; i < 4; ++i) {
;     const int row = (i * 4 + wave) * 8 + (lane >> 3), chunk = (lane & 7) ^ ((row >> 1) & 7);
;     __builtin_amdgcn_global_load_lds((const unsigned*)(A + (size_t)(m0 + row) * lda + chunk * 8), LDSP(unsigned, smem + (i * 4 + wave) * 1024), 16, 0, 0);
;     __builtin_amdgcn_global_load_lds((const unsigned*)(Bt + (size_t)(n0 + row) * ldb + chunk * 8), LDSP(unsigned, smem + 16384 + (i * 4 + wave) * 1024), 16, 0, 0);
;   }
; }
; template <int EPI>
; DI void gemm_phase(const GArgs& g, char* smem) {
;   const int ntm = g.M / 128, ntn = g.Npad / 128;
;   const int tid = tidx(), lane = tid & 63, wave = tid >> 6;
;   if ((int)blockIdx.x < ntm * ntn) gemm_issue_first(g.A, g.lda, g.Bt, g.K, (blockIdx.x % ntm) * 128, (blockIdx.x / ntm) * 128, smem);
;   for (int tile = blockIdx.x; tile < ntm * ntn; tile += gridDim.x) {
;     const int m0 = (tile % ntm) * 128, n0 = (tile / ntm) * 128;
.LBB0_356:
	v_mov_b32_e32 v2, v190
	s_sub_u32 s100, s82, 0x80
	s_cmp_gt_u32 s100, 15
	s_cbranch_scc1 .LBB0_367
	v_mov_b32_e32 v3, v190
	v_readlane_b32 s3, v253, 8
	v_ashrrev_i32_e32 v6, 6, v3
	v_bfe_u32 v7, v3, 3, 3
	v_lshl_or_b32 v8, v6, 3, v7
	v_lshrrev_b32_e32 v0, 1, v8
	v_add_u32_e32 v4, s3, v8
	s_lshl_b64 s[0:1], s[80:81], 13
	v_readlane_b32 s2, v250, 58
	v_xor_b32_e32 v0, v0, v3
	v_ashrrev_i32_e32 v5, 31, v4
	v_readlane_b32 s4, v252, 57
	s_add_u32 s0, s2, s0
	v_readlane_b32 s2, v250, 59
	v_lshlrev_b64 v[4:5], 13, v[4:5]
	v_readlane_b32 s5, v252, 58
	v_lshlrev_b32_e32 v0, 4, v0
	v_lshlrev_b32_e32 v9, 10, v6
	s_addc_u32 s1, s2, s1
	v_lshl_add_u64 v[4:5], s[4:5], 0, v[4:5]
	v_and_b32_e32 v0, 0x70, v0
	v_readfirstlane_b32 s2, v9
	v_lshl_add_u64 v[4:5], v[4:5], 0, v[0:1]
	s_mov_b32 m0, s2
	s_mov_b32 s6, 0
	global_load_lds_dwordx4 v[4:5], off
	s_nop 0
	v_add_u32_e32 v4, s6, v8
	v_ashrrev_i32_e32 v5, 31, v4
	v_lshlrev_b64 v[4:5], 13, v[4:5]
	v_lshl_add_u64 v[4:5], s[0:1], 0, v[4:5]
	v_lshl_add_u64 v[4:5], v[4:5], 0, v[0:1]
	v_add_u32_e32 v0, 0x4000, v9
	v_add_u32_e32 v8, 4, v6
	v_readfirstlane_b32 s2, v0
	s_mov_b32 m0, s2
	v_lshl_or_b32 v9, v8, 3, v7
	global_load_lds_dwordx4 v[4:5], off
	v_lshrrev_b32_e32 v0, 1, v9
	v_add_u32_e32 v4, s3, v9
	v_xor_b32_e32 v0, v0, v3
	v_ashrrev_i32_e32 v5, 31, v4
	v_lshlrev_b64 v[4:5], 13, v[4:5]
	v_lshlrev_b32_e32 v0, 4, v0
	v_lshlrev_b32_e32 v8, 10, v8
	v_lshl_add_u64 v[4:5], s[4:5], 0, v[4:5]
	v_and_b32_e32 v0, 0x70, v0
	v_readfirstlane_b32 s2, v8
	v_lshl_add_u64 v[4:5], v[4:5], 0, v[0:1]
	s_mov_b32 m0, s2
	s_nop 0
	global_load_lds_dwordx4 v[4:5], off
	v_add_u32_e32 v4, s6, v9
	v_ashrrev_i32_e32 v5, 31, v4
	v_lshlrev_b64 v[4:5], 13, v[4:5]
	v_lshl_add_u64 v[4:5], s[0:1], 0, v[4:5]
	v_lshl_add_u64 v[4:5], v[4:5], 0, v[0:1]
	v_add_u32_e32 v0, 0x4000, v8
	v_add_u32_e32 v8, 8, v6
	v_readfirstlane_b32 s2, v0
	s_mov_b32 m0, s2
	v_lshl_or_b32 v9, v8, 3, v7
	global_load_lds_dwordx4 v[4:5], off
	v_lshrrev_b32_e32 v0, 1, v9
	v_add_u32_e32 v4, s3, v9
	v_xor_b32_e32 v0, v0, v3
	v_ashrrev_i32_e32 v5, 31, v4
	v_lshlrev_b64 v[4:5], 13, v[4:5]
	v_lshlrev_b32_e32 v0, 4, v0
	v_lshlrev_b32_e32 v8, 10, v8
	v_lshl_add_u64 v[4:5], s[4:5], 0, v[4:5]
	v_and_b32_e32 v0, 0x70, v0
	v_readfirstlane_b32 s2, v8
	v_lshl_add_u64 v[4:5], v[4:5], 0, v[0:1]
	s_mov_b32 m0, s2
	v_add_u32_e32 v6, 12, v6
	global_load_lds_dwordx4 v[4:5], off
	v_add_u32_e32 v4, s6, v9
	v_ashrrev_i32_e32 v5, 31, v4
	v_lshlrev_b64 v[4:5], 13, v[4:5]
	v_lshl_add_u64 v[4:5], s[0:1], 0, v[4:5]
	v_lshl_add_u64 v[4:5], v[4:5], 0, v[0:1]
	v_add_u32_e32 v0, 0x4000, v8
	v_lshl_or_b32 v7, v6, 3, v7
	v_readfirstlane_b32 s2, v0
	s_mov_b32 m0, s2
	v_lshrrev_b32_e32 v0, 1, v7
	global_load_lds_dwordx4 v[4:5], off
	v_add_u32_e32 v4, s3, v7
	v_xor_b32_e32 v0, v0, v3
	v_ashrrev_i32_e32 v5, 31, v4
	v_lshlrev_b64 v[4:5], 13, v[4:5]
	v_lshlrev_b32_e32 v0, 4, v0
	v_lshlrev_b32_e32 v3, 10, v6
	v_lshl_add_u64 v[4:5], s[4:5], 0, v[4:5]
	v_and_b32_e32 v0, 0x70, v0
	v_readfirstlane_b32 s2, v3
	v_lshl_add_u64 v[4:5], v[4:5], 0, v[0:1]
	s_mov_b32 m0, s2
	s_mov_b32 s4, s100
	global_load_lds_dwordx4 v[4:5], off
	v_add_u32_e32 v4, s6, v7
	v_ashrrev_i32_e32 v5, 31, v4
	v_lshlrev_b64 v[4:5], 13, v[4:5]
	v_lshl_add_u64 v[4:5], s[0:1], 0, v[4:5]
	v_lshl_add_u64 v[4:5], v[4:5], 0, v[0:1]
	v_add_u32_e32 v0, 0x4000, v3
	v_and_b32_e32 v3, 15, v2
	v_readfirstlane_b32 s2, v0
	s_mov_b32 m0, s2
	v_ashrrev_i32_e32 v0, 1, v2
	global_load_lds_dwordx4 v[4:5], off
	s_movk_i32 s2, 0xffe0
	v_and_or_b32 v166, v0, s2, v3
	v_lshrrev_b32_e32 v0, 2, v2
	v_and_b32_e32 v167, 12, v0
	s_branch .LBB0_359

; __global__ void __launch_bounds__(256, 2) mega(Params p) {
;   cg::grid_group grid = cg::this_grid();
;   __shared__ __attribute__((aligned(16))) char smem[65536 + 16];
	.amdhsa_kernel _Z4mega6Params
		.amdhsa_group_segment_fixed_size 65552
		.amdhsa_private_segment_fixed_size 0
		.amdhsa_kernarg_size 496
		.amdhsa_user_sgpr_count 2
		.amdhsa_user_sgpr_dispatch_ptr 0
		.amdhsa_user_sgpr_queue_ptr 0
		.amdhsa_user_sgpr_kernarg_segment_ptr 1
		.amdhsa_user_sgpr_dispatch_id 0
		.amdhsa_user_sgpr_kernarg_preload_length 0
		.amdhsa_user_sgpr_kernarg_preload_offset 0
		.amdhsa_user_sgpr_private_segment_size 0
		.amdhsa_uses_dynamic_stack 0
		.amdhsa_enable_private_segment 0
		.amdhsa_system_sgpr_workgroup_id_x 1
		.amdhsa_system_sgpr_workgroup_id_y 0
		.amdhsa_system_sgpr_workgroup_id_z 0
		.amdhsa_system_sgpr_workgroup_info 0
		.amdhsa_system_vgpr_workitem_id 2
		.amdhsa_next_free_vgpr 256
		.amdhsa_next_free_sgpr 102
		.amdhsa_accum_offset 256
		.amdhsa_reserve_vcc 1
		.amdhsa_float_round_mode_32 0
		.amdhsa_float_round_mode_16_64 0
		.amdhsa_float_denorm_mode_32 3
		.amdhsa_float_denorm_mode_16_64 3
		.amdhsa_dx10_clamp 1
		.amdhsa_ieee_mode 1
		.amdhsa_fp16_overflow 0
		.amdhsa_tg_split 0
		.amdhsa_exception_fp_ieee_invalid_op 0
		.amdhsa_exception_fp_denorm_src 0
		.amdhsa_exception_fp_ieee_div_zero 0
		.amdhsa_exception_fp_ieee_overflow 0
		.amdhsa_exception_fp_ieee_underflow 0
		.amdhsa_exception_fp_ieee_inexact 0
		.amdhsa_exception_int_div_zero 0
	.end_amdhsa_kernel

; __global__ void __launch_bounds__(256, 2) mega(Params p) {
;   cg::grid_group grid = cg::this_grid();
;   __shared__ __attribute__((aligned(16))) char smem[65536 + 16];
amdhsa.kernels:
  - .agpr_count:     0
    .args:
      - .offset:         0
        .size:           240
        .value_kind:     by_value
      - .offset:         240
        .size:           4
        .value_kind:     hidden_block_count_x
      - .offset:         244
        .size:           4
        .value_kind:     hidden_block_count_y
      - .offset:         248
        .size:           4
        .value_kind:     hidden_block_count_z
      - .offset:         252
        .size:           2
        .value_kind:     hidden_group_size_x
      - .offset:         254
        .size:           2
        .value_kind:     hidden_group_size_y
      - .offset:         256
        .size:           2
        .value_kind:     hidden_group_size_z
      - .offset:         258
        .size:           2
        .value_kind:     hidden_remainder_x
      - .offset:         260
        .size:           2
        .value_kind:     hidden_remainder_y
      - .offset:         262
        .size:           2
        .value_kind:     hidden_remainder_z
      - .offset:         280
        .size:           8
        .value_kind:     hidden_global_offset_x
      - .offset:         288
        .size:           8
        .value_kind:     hidden_global_offset_y
      - .offset:         296
        .size:           8
        .value_kind:     hidden_global_offset_z
      - .offset:         304
        .size:           2
        .value_kind:     hidden_grid_dims
      - .offset:         328
        .size:           8
        .value_kind:     hidden_multigrid_sync_arg
    .group_segment_fixed_size: 65552
    .kernarg_segment_align: 8
    .kernarg_segment_size: 496
    .language:       OpenCL C
    .language_version:
      - 2
      - 0
    .max_flat_workgroup_size: 256
    .name:           _Z4mega6Params
    .private_segment_fixed_size: 0
    .sgpr_count:     108
    .sgpr_spill_count: 372
    .symbol:         _Z4mega6Params.kd
    .uniform_work_group_size: 1
    .uses_dynamic_stack: false
    .vgpr_count:     256
    .vgpr_spill_count: 0
    .wavefront_size: 64
